# up phase tile loop: barrier at the tile top no longer drains the previous tile's stores
# baseline (speedup 1.0000x reference)
.LBB0_565:
	s_cmpk_gt_i32 s16, 0x23f
	s_waitcnt lgkmcnt(0)
	s_barrier
	s_cbranch_scc0 .LBB0_579
	s_cmpk_gt_u32 s16, 0x3ff
	s_mov_b64 s[0:1], -1
	s_cbranch_scc0 .LBB0_576
	s_cmpk_gt_u32 s16, 0x5bf
	s_cbranch_scc0 .LBB0_573
	s_cmpk_gt_u32 s16, 0x6bf
	s_cbranch_scc0 .LBB0_570
	s_add_i32 s1, s16, 0xfffff940
	s_bfe_u32 s0, s16, 0x10004
	s_lshr_b32 s96, s1, 5
	s_lshl_b32 s4, s0, 15
	s_add_u32 s4, s80, s4
	s_addc_u32 s5, s81, 0
	s_and_b32 s10, s15, 0x7ffff800
	s_addk_i32 s10, 0x1000
	s_mul_hi_u32 s11, s10, 0x1c00
	s_mulk_i32 s10, 0x1c00
	s_add_u32 s10, s90, s10
	s_addc_u32 s11, s91, s11
	s_lshl_b32 s1, s1, 3
	s_and_b32 s1, s1, 0x300
	v_mov_b32_e32 v54, v206
	s_add_u32 s1, s10, s1
	s_addc_u32 s11, s11, 0
	v_ashrrev_i32_e32 v34, 3, v54
	v_ashrrev_i32_e32 v35, 31, v34
	s_add_u32 s10, s1, 0x1680
	v_lshlrev_b64 v[2:3], 8, v[34:35]
	v_lshlrev_b32_e32 v0, 4, v54
	s_addc_u32 s11, s11, 0
	s_and_b32 s1, s14, 0x780
	v_lshl_add_u64 v[2:3], s[4:5], 0, v[2:3]
	v_and_b32_e32 v0, 0x70, v0
	v_lshl_add_u64 v[18:19], v[2:3], 0, v[0:1]
	v_add_u32_e32 v2, s1, v34
	v_min_i32_e32 v4, 0x7ff, v2
	v_min_i32_e32 v2, 0x7bf, v2
	v_add_u32_e32 v6, 64, v2
	v_mov_b64_e32 v[2:3], s[10:11]
	s_movk_i32 s10, 0x1c00
	v_mad_i64_i32 v[4:5], s[4:5], v4, s10, v[2:3]
	v_mad_i64_i32 v[2:3], s[4:5], v6, s10, v[2:3]
	s_movk_i32 s4, 0x4000
	s_nop 0
	v_add_co_u32_e32 v22, vcc, s4, v18
	v_lshl_add_u64 v[26:27], v[4:5], 0, v[0:1]
	v_lshl_add_u64 v[30:31], v[2:3], 0, v[0:1]
	v_addc_co_u32_e32 v23, vcc, 0, v19, vcc
	global_load_dwordx4 v[2:5], v[18:19], off
	global_load_dwordx4 v[6:9], v[22:23], off
	global_load_dwordx4 v[10:13], v[26:27], off
	global_load_dwordx4 v[14:17], v[30:31], off
	v_lshrrev_b32_e32 v20, 4, v54
	v_bfe_u32 v55, v54, 1, 3
	v_xor_b32_e32 v32, v20, v54
	v_bitop3_b32 v35, v20, v55, 3 bitop3:0x6c
	global_load_dwordx4 v[18:21], v[18:19], off offset:128
	s_nop 0
	global_load_dwordx4 v[22:25], v[22:23], off offset:128
	s_nop 0
	global_load_dwordx4 v[26:29], v[26:27], off offset:128
	v_lshlrev_b32_e32 v36, 4, v32
	global_load_dwordx4 v[30:33], v[30:31], off offset:128
	v_bfe_u32 v0, v54, 6, 2
	v_and_b32_e32 v67, 15, v54
	v_lshlrev_b32_e32 v58, 7, v67
	v_lshlrev_b32_e32 v56, 12, v0
	v_lshlrev_b32_e32 v35, 4, v35
	v_and_b32_e32 v36, 0x70, v36
	v_or3_b32 v68, v35, v56, v58
	v_lshl_or_b32 v69, v34, 7, v36
	v_ashrrev_i32_e32 v66, 8, v54
	v_bfe_u32 v71, v54, 4, 2
	v_lshlrev_b32_e32 v59, 13, v66
	v_bitop3_b32 v54, v71, v55, 4 bitop3:0x36
	v_or3_b32 v70, v35, v59, v58
	v_lshlrev_b32_e32 v60, 4, v54
	v_or3_b32 v72, v60, v56, v58
	v_or3_b32 v73, v60, v59, v58
	v_readlane_b32 s36, v253, 33
	s_lshl_b64 s[4:5], s[96:97], 20
	v_readlane_b32 s46, v253, 43
	v_readlane_b32 s47, v253, 44
	s_add_u32 s4, s46, s4
	v_lshlrev_b32_e32 v0, 5, v0
	s_addc_u32 s5, s47, s5
	s_lshl_b32 s0, s0, 12
	s_add_u32 s4, s4, s0
	s_addc_u32 s5, s5, 0
	v_readlane_b32 s96, v254, 51
	v_readlane_b32 s37, v253, 34
	v_readlane_b32 s38, v253, 35
	v_readlane_b32 s39, v253, 36
	v_readlane_b32 s40, v253, 37
	v_readlane_b32 s41, v253, 38
	v_readlane_b32 s42, v253, 39
	v_readlane_b32 s43, v253, 40
	v_readlane_b32 s44, v253, 41
	v_readlane_b32 s45, v253, 42
	v_readlane_b32 s48, v253, 45
	v_readlane_b32 s49, v253, 46
	v_readlane_b32 s50, v253, 47
	v_readlane_b32 s51, v253, 48
	s_waitcnt vmcnt(7)
	ds_write_b128 v69, v[2:5]
	s_waitcnt vmcnt(6)
	ds_write_b128 v69, v[6:9] offset:8192
	s_waitcnt vmcnt(5)
	ds_write_b128 v69, v[10:13] offset:32768
	s_waitcnt vmcnt(4)
	ds_write_b128 v69, v[14:17] offset:40960
	s_waitcnt lgkmcnt(0)
	s_barrier
	ds_read_b128 v[2:5], v68 offset:32768
	ds_read_b128 v[6:9], v68 offset:34816
	ds_read_b128 v[10:13], v70
	ds_read_b128 v[14:17], v70 offset:2048
	ds_read_b128 v[42:45], v70 offset:4096
	ds_read_b128 v[46:49], v70 offset:6144
	ds_read_b128 v[54:57], v72 offset:32768
	ds_read_b128 v[58:61], v72 offset:34816
	s_waitcnt lgkmcnt(5)
	v_mfma_f32_16x16x32_bf16 v[34:37], v[2:5], v[10:13], 0
	v_mfma_f32_16x16x32_bf16 v[10:13], v[6:9], v[10:13], 0
	s_waitcnt lgkmcnt(4)
	v_mfma_f32_16x16x32_bf16 v[38:41], v[2:5], v[14:17], 0
	v_mfma_f32_16x16x32_bf16 v[14:17], v[6:9], v[14:17], 0
	s_waitcnt lgkmcnt(3)
	v_mfma_f32_16x16x32_bf16 v[50:53], v[2:5], v[42:45], 0
	v_mfma_f32_16x16x32_bf16 v[42:45], v[6:9], v[42:45], 0
	s_waitcnt lgkmcnt(2)
	v_mfma_f32_16x16x32_bf16 v[2:5], v[2:5], v[46:49], 0
	v_mfma_f32_16x16x32_bf16 v[6:9], v[6:9], v[46:49], 0
	ds_read_b128 v[46:49], v73
	ds_read_b128 v[62:65], v73 offset:2048
	s_waitcnt lgkmcnt(1)
	v_mfma_f32_16x16x32_bf16 v[34:37], v[54:57], v[46:49], v[34:37]
	v_mfma_f32_16x16x32_bf16 v[10:13], v[58:61], v[46:49], v[10:13]
	s_waitcnt lgkmcnt(0)
	v_mfma_f32_16x16x32_bf16 v[38:41], v[54:57], v[62:65], v[38:41]
	v_mfma_f32_16x16x32_bf16 v[14:17], v[58:61], v[62:65], v[14:17]
	ds_read_b128 v[46:49], v73 offset:4096
	ds_read_b128 v[62:65], v73 offset:6144
	s_waitcnt vmcnt(3)
	ds_write_b128 v69, v[18:21] offset:16384
	s_waitcnt vmcnt(2)
	ds_write_b128 v69, v[22:25] offset:24576
	s_waitcnt vmcnt(1)
	ds_write_b128 v69, v[26:29] offset:49152
	s_waitcnt vmcnt(0)
	ds_write_b128 v69, v[30:33] offset:57344
	s_waitcnt lgkmcnt(0)
	s_barrier
	ds_read_b128 v[22:25], v68 offset:49152
	v_mfma_f32_16x16x32_bf16 v[18:21], v[58:61], v[46:49], v[42:45]
	ds_read_b128 v[26:29], v68 offset:51200
	ds_read_b128 v[30:33], v70 offset:16384
	s_nop 0
	ds_read_b128 v[42:45], v70 offset:18432
	s_waitcnt lgkmcnt(1)
	v_mfma_f32_16x16x32_bf16 v[34:37], v[22:25], v[30:33], v[34:37]
	v_mfma_f32_16x16x32_bf16 v[10:13], v[26:29], v[30:33], v[10:13]
	s_waitcnt lgkmcnt(0)
	v_mfma_f32_16x16x32_bf16 v[30:33], v[22:25], v[42:45], v[38:41]
	v_mfma_f32_16x16x32_bf16 v[14:17], v[26:29], v[42:45], v[14:17]
	s_nop 1
	ds_read_b128 v[38:41], v70 offset:20480
	ds_read_b128 v[42:45], v70 offset:22528
	v_mfma_f32_16x16x32_bf16 v[50:53], v[54:57], v[46:49], v[50:53]
	v_mfma_f32_16x16x32_bf16 v[2:5], v[54:57], v[62:65], v[2:5]
	v_mfma_f32_16x16x32_bf16 v[6:9], v[58:61], v[62:65], v[6:9]
	s_waitcnt lgkmcnt(1)
	v_mfma_f32_16x16x32_bf16 v[46:49], v[22:25], v[38:41], v[50:53]
	s_waitcnt lgkmcnt(0)
	v_mfma_f32_16x16x32_bf16 v[2:5], v[22:25], v[42:45], v[2:5]
	ds_read_b128 v[22:25], v72 offset:49152
	v_mfma_f32_16x16x32_bf16 v[18:21], v[26:29], v[38:41], v[18:21]
	v_mfma_f32_16x16x32_bf16 v[6:9], v[26:29], v[42:45], v[6:9]
	ds_read_b128 v[26:29], v72 offset:51200
	ds_read_b128 v[38:41], v73 offset:16384
	ds_read_b128 v[42:45], v73 offset:18432
	s_waitcnt lgkmcnt(1)
	v_mfma_f32_16x16x32_bf16 v[34:37], v[22:25], v[38:41], v[34:37]
	v_mfma_f32_16x16x32_bf16 v[10:13], v[26:29], v[38:41], v[10:13]
	s_waitcnt lgkmcnt(0)
	v_mfma_f32_16x16x32_bf16 v[30:33], v[22:25], v[42:45], v[30:33]
	v_mfma_f32_16x16x32_bf16 v[14:17], v[26:29], v[42:45], v[14:17]
	ds_read_b128 v[38:41], v73 offset:20480
	ds_read_b128 v[42:45], v73 offset:22528
	s_nop 2
	v_cvt_pk_bf16_f32 v10, v10, v11
	v_cvt_pk_bf16_f32 v11, v12, v13
	s_waitcnt lgkmcnt(1)
	v_mfma_f32_16x16x32_bf16 v[46:49], v[22:25], v[38:41], v[46:49]
	s_waitcnt lgkmcnt(0)
	v_mfma_f32_16x16x32_bf16 v[22:25], v[22:25], v[42:45], v[2:5]
	v_mfma_f32_16x16x32_bf16 v[2:5], v[26:29], v[42:45], v[6:9]
	s_nop 2
	v_lshlrev_b32_e32 v6, 2, v71
	v_or3_b32 v0, v0, v6, s1
	v_lshl_or_b32 v6, v66, 6, v67
	v_ashrrev_i32_e32 v7, 31, v6
	v_lshlrev_b64 v[8:9], 13, v[6:7]
	v_lshl_add_u64 v[8:9], s[4:5], 0, v[8:9]
	v_lshlrev_b32_e32 v0, 1, v0
	v_mfma_f32_16x16x32_bf16 v[18:21], v[26:29], v[38:41], v[18:21]
	v_cvt_pk_bf16_f32 v26, v34, v35
	v_cvt_pk_bf16_f32 v27, v36, v37
	v_lshl_add_u64 v[8:9], v[8:9], 0, v[0:1]
	global_store_dwordx2 v[8:9], v[26:27], off
	global_store_dwordx2 v[8:9], v[10:11], off offset:32
	v_or_b32_e32 v8, 16, v6
	v_ashrrev_i32_e32 v9, 31, v8
	v_lshlrev_b64 v[8:9], 13, v[8:9]
	v_lshl_add_u64 v[8:9], s[4:5], 0, v[8:9]
	v_cvt_pk_bf16_f32 v10, v30, v31
	v_cvt_pk_bf16_f32 v11, v32, v33
	v_lshl_add_u64 v[8:9], v[8:9], 0, v[0:1]
	global_store_dwordx2 v[8:9], v[10:11], off
	v_cvt_pk_bf16_f32 v10, v14, v15
	v_cvt_pk_bf16_f32 v11, v16, v17
	global_store_dwordx2 v[8:9], v[10:11], off offset:32
	v_or_b32_e32 v8, 32, v6
	v_ashrrev_i32_e32 v9, 31, v8
	v_lshlrev_b64 v[8:9], 13, v[8:9]
	v_or_b32_e32 v6, 48, v6
	v_lshl_add_u64 v[8:9], s[4:5], 0, v[8:9]
	v_ashrrev_i32_e32 v7, 31, v6
	v_cvt_pk_bf16_f32 v10, v46, v47
	v_cvt_pk_bf16_f32 v11, v48, v49
	v_lshl_add_u64 v[8:9], v[8:9], 0, v[0:1]
	v_lshlrev_b64 v[6:7], 13, v[6:7]
	global_store_dwordx2 v[8:9], v[10:11], off
	v_cvt_pk_bf16_f32 v10, v18, v19
	v_cvt_pk_bf16_f32 v11, v20, v21
	v_lshl_add_u64 v[6:7], s[4:5], 0, v[6:7]
	global_store_dwordx2 v[8:9], v[10:11], off offset:32
	v_cvt_pk_bf16_f32 v8, v22, v23
	v_cvt_pk_bf16_f32 v9, v24, v25
	v_lshl_add_u64 v[10:11], v[6:7], 0, v[0:1]
	v_cvt_pk_bf16_f32 v0, v2, v3
	global_store_dwordx2 v[10:11], v[8:9], off
	v_lshl_add_u64 v[6:7], v[10:11], 0, 32
	global_store_dword v[10:11], v0, off offset:32
	s_mov_b64 s[0:1], 0
